# in-projection q/k norm epilogue (head dim 128): the rotary-table rows of the next seven row groups are touched with one small load each before the first row, so the per-row table loads hit the L1
# speedup vs baseline: 1.0101x; 1.0048x over previous
.LBB0_627:
	s_or_b64 exec, exec, s[8:9]
	v_add_u32_e32 v175, s27, v223
	v_lshlrev_b32_e32 v182, 2, v175
	v_bitop3_b32 v182, v182, 1, s26 bitop3:0x36
	v_lshl_add_u32 v182, v182, 2, 0
	s_waitcnt lgkmcnt(0)
	s_barrier
	v_add_u32_e32 v182, 0x20000, v182
	ds_read_b32 v186, v182
	v_pk_mul_f32 v[184:185], v[128:129], v[158:159] op_sel_hi:[1,0]
	v_pk_mul_f32 v[188:189], v[126:127], v[158:159] op_sel_hi:[1,0]
	v_readlane_b32 s0, v255, 48
	v_pk_mul_f32 v[192:193], v[124:125], v[158:159] op_sel_hi:[1,0]
	s_waitcnt lgkmcnt(0)
	v_add_f32_e32 v183, v183, v186
	v_fmamk_f32 v183, v183, 0x3c000000, v254
	v_rsq_f32_e32 v186, v183
	v_pk_mul_f32 v[196:197], v[122:123], v[158:159] op_sel_hi:[1,0]
	v_readlane_b32 s1, v255, 49
	v_add_u32_e32 v182, s47, v175
	v_pk_mul_f32 v[188:189], v[188:189], v[186:187] op_sel_hi:[1,0]
	v_pk_mul_f32 v[184:185], v[184:185], v[186:187] op_sel_hi:[1,0]
	v_pk_mul_f32 v[192:193], v[192:193], v[186:187] op_sel_hi:[1,0]
	s_waitcnt vmcnt(3)
	v_pk_mul_f32 v[190:191], v[144:145], v[184:185]
	v_pk_mul_f32 v[184:185], v[142:143], v[188:189]
	v_pk_mul_f32 v[188:189], v[196:197], v[186:187] op_sel_hi:[1,0]
	v_cndmask_b32_e64 v183, 0, 1, s[0:1]
	s_waitcnt vmcnt(2)
	v_pk_mul_f32 v[192:193], v[140:141], v[192:193]
	v_pk_mul_f32 v[188:189], v[138:139], v[188:189]
	v_cmp_ne_u32_e64 s[8:9], 1, v183
	s_andn2_b64 vcc, exec, s[0:1]
	v_ashrrev_i32_e32 v183, 31, v182
	s_cbranch_vccnz .LBB0_629
	v_readlane_b32 s0, v255, 30
	v_lshlrev_b64 v[196:197], 7, v[182:183]
	v_readlane_b32 s1, v255, 31
	s_nop 1
	v_lshl_add_u64 v[196:197], s[0:1], 0, v[196:197]
	v_lshl_add_u64 v[200:201], v[180:181], 2, v[196:197]
	global_load_dword v244, v[200:201], off offset:2048
	v_mov_b32_e32 v212, 0x1000
	v_mov_b32_e32 v213, 0
	v_lshl_add_u64 v[226:227], v[212:213], 0, v[200:201]
	global_load_dword v245, v[226:227], off
	global_load_dword v246, v[226:227], off offset:2048
	v_mov_b32_e32 v212, 0x4000
	v_lshl_add_u64 v[226:227], v[212:213], 0, v[200:201]
	global_load_dword v247, v[226:227], off
	global_load_dword v248, v[226:227], off offset:2048
	v_mov_b32_e32 v212, 0x5000
	v_lshl_add_u64 v[226:227], v[212:213], 0, v[200:201]
	global_load_dword v249, v[226:227], off
	global_load_dword v250, v[226:227], off offset:2048
	global_load_dwordx4 v[196:199], v[200:201], off offset:16
	global_load_dwordx4 v[240:243], v[200:201], off
	s_waitcnt vmcnt(1)
	v_mul_f32_e32 v208, v190, v196
	v_mul_f32_e32 v210, v192, v197
	v_mul_f32_e32 v196, v192, v196
	v_mov_b32_e32 v192, v191
	s_waitcnt vmcnt(0)
	v_mov_b32_e32 v201, v242
	v_mov_b32_e32 v242, v241
	v_mul_f32_e32 v214, v190, v197
	v_pk_mul_f32 v[216:217], v[192:193], v[198:199]
	v_mov_b32_e32 v190, v193
	v_mov_b32_e32 v200, v240
	v_pk_mul_f32 v[204:205], v[188:189], v[242:243]
	v_mov_b32_e32 v209, v216
	v_mov_b32_e32 v211, v217
	v_pk_mul_f32 v[190:191], v[190:191], v[198:199]
	v_pk_mul_f32 v[206:207], v[184:185], v[242:243]
	v_pk_fma_f32 v[184:185], v[184:185], v[200:201], v[204:205] neg_lo:[0,0,1] neg_hi:[0,0,1]
	v_pk_add_f32 v[204:205], v[208:209], v[210:211] neg_lo:[0,1] neg_hi:[0,1]
	v_mov_b32_e32 v197, v190
	v_mov_b32_e32 v215, v191
	v_pk_fma_f32 v[188:189], v[188:189], v[200:201], v[206:207]
	v_pk_add_f32 v[192:193], v[196:197], v[214:215]
	v_mov_b32_e32 v190, v204
	v_mov_b32_e32 v191, v205

.LBB0_662:
	s_or_b64 exec, exec, s[8:9]
	v_add_u32_e32 v175, s27, v223
	v_lshlrev_b32_e32 v182, 2, v175
	v_bitop3_b32 v182, v182, 1, s26 bitop3:0x36
	v_lshl_add_u32 v182, v182, 2, 0
	s_waitcnt lgkmcnt(0)
	s_barrier
	v_add_u32_e32 v182, 0x20000, v182
	ds_read_b32 v184, v182
	s_mov_b32 s0, 0x3e0293ee
	s_waitcnt vmcnt(3)
	v_pk_mul_f32 v[144:145], v[144:145], s[0:1] op_sel_hi:[1,0]
	v_pk_mul_f32 v[142:143], v[142:143], s[0:1] op_sel_hi:[1,0]
	s_waitcnt vmcnt(2)
	v_pk_mul_f32 v[140:141], v[140:141], s[0:1] op_sel_hi:[1,0]
	s_waitcnt lgkmcnt(0)
	v_add_f32_e32 v183, v183, v184
	v_fmamk_f32 v183, v183, 0x3c000000, v254
	v_rsq_f32_e32 v184, v183
	v_pk_mul_f32 v[138:139], v[138:139], s[0:1] op_sel_hi:[1,0]
	v_pk_mul_f32 v[186:187], v[128:129], v[158:159] op_sel_hi:[1,0]
	v_pk_mul_f32 v[188:189], v[126:127], v[158:159] op_sel_hi:[1,0]
	v_readlane_b32 s0, v255, 48
	v_pk_mul_f32 v[192:193], v[124:125], v[158:159] op_sel_hi:[1,0]
	v_pk_mul_f32 v[196:197], v[122:123], v[158:159] op_sel_hi:[1,0]
	v_pk_mul_f32 v[188:189], v[188:189], v[184:185] op_sel_hi:[1,0]
	v_pk_mul_f32 v[186:187], v[186:187], v[184:185] op_sel_hi:[1,0]
	v_readlane_b32 s1, v255, 49
	v_add_u32_e32 v182, s47, v175
	v_pk_mul_f32 v[190:191], v[144:145], v[186:187]
	v_pk_mul_f32 v[186:187], v[142:143], v[188:189]
	v_pk_mul_f32 v[188:189], v[196:197], v[184:185] op_sel_hi:[1,0]
	v_pk_mul_f32 v[192:193], v[192:193], v[184:185] op_sel_hi:[1,0]
	v_cndmask_b32_e64 v183, 0, 1, s[0:1]
	v_pk_mul_f32 v[192:193], v[140:141], v[192:193]
	v_pk_mul_f32 v[188:189], v[138:139], v[188:189]
	v_cmp_ne_u32_e64 s[8:9], 1, v183
	s_andn2_b64 vcc, exec, s[0:1]
	v_ashrrev_i32_e32 v183, 31, v182
	s_cbranch_vccnz .LBB0_664
	v_readlane_b32 s0, v255, 30
	v_lshlrev_b64 v[196:197], 7, v[182:183]
	v_readlane_b32 s1, v255, 31
	s_nop 1
	v_lshl_add_u64 v[196:197], s[0:1], 0, v[196:197]
	v_lshl_add_u64 v[200:201], v[180:181], 2, v[196:197]
	global_load_dword v244, v[200:201], off offset:2048
	v_mov_b32_e32 v212, 0x1000
	v_mov_b32_e32 v213, 0
	v_lshl_add_u64 v[226:227], v[212:213], 0, v[200:201]
	global_load_dword v245, v[226:227], off
	global_load_dword v246, v[226:227], off offset:2048
	v_mov_b32_e32 v212, 0x4000
	v_lshl_add_u64 v[226:227], v[212:213], 0, v[200:201]
	global_load_dword v247, v[226:227], off
	global_load_dword v248, v[226:227], off offset:2048
	v_mov_b32_e32 v212, 0x5000
	v_lshl_add_u64 v[226:227], v[212:213], 0, v[200:201]
	global_load_dword v249, v[226:227], off
	global_load_dword v250, v[226:227], off offset:2048
	global_load_dwordx4 v[196:199], v[200:201], off offset:16
	global_load_dwordx4 v[240:243], v[200:201], off
	s_waitcnt vmcnt(1)
	v_mul_f32_e32 v208, v190, v196
	v_mul_f32_e32 v210, v192, v197
	v_mul_f32_e32 v196, v192, v196
	v_mov_b32_e32 v192, v191
	s_waitcnt vmcnt(0)
	v_mov_b32_e32 v201, v242
	v_mov_b32_e32 v242, v241
	v_mul_f32_e32 v214, v190, v197
	v_pk_mul_f32 v[216:217], v[192:193], v[198:199]
	v_mov_b32_e32 v190, v193
	v_mov_b32_e32 v200, v240
	v_pk_mul_f32 v[204:205], v[188:189], v[242:243]
	v_mov_b32_e32 v209, v216
	v_mov_b32_e32 v211, v217
	v_pk_mul_f32 v[190:191], v[190:191], v[198:199]
	v_pk_mul_f32 v[206:207], v[186:187], v[242:243]
	v_pk_fma_f32 v[186:187], v[186:187], v[200:201], v[204:205] neg_lo:[0,0,1] neg_hi:[0,0,1]
	v_pk_add_f32 v[204:205], v[208:209], v[210:211] neg_lo:[0,1] neg_hi:[0,1]
	v_mov_b32_e32 v197, v190
	v_mov_b32_e32 v215, v191
	v_pk_fma_f32 v[188:189], v[188:189], v[200:201], v[206:207]
	v_pk_add_f32 v[192:193], v[196:197], v[214:215]
	v_mov_b32_e32 v190, v204
	v_mov_b32_e32 v191, v205
